# nt hints: final RMSNorm output stores and retention-scan KV loads
# speedup vs baseline: 1.0091x; 1.0017x over previous
; __device__ __forceinline__ unsigned pk2(float lo, float hi) { f32x2 f = {lo, hi}; bf16x2_t b = __builtin_convertvector(f, bf16x2_t); return __builtin_bit_cast(unsigned, b); }
; __device__ __forceinline__ float ret_log2g(int h) { const double g = 1.0 - ldexp(1.0, -(5 + h)); return (float)log2(g); }
; __global__ void __launch_bounds__(512, 2) mega_fwd(Params p) {
;     ...
;         for (int idx = blockIdx.x * 512 + tid; idx < 16 * 32768; idx += G * 512) {
;             const int bh = idx >> 15, ed = idx & 32767, h = bh & 7;
;             const float decay = __builtin_amdgcn_exp2f(128.0f * ret_log2g(h));
;             const float* kv = P_KV + (size_t)bh * 32 * 32768 + ed;
;             const int e_ = ed >> 7, d_ = ed & 127;
;             const int foff = ((((e_ >> 7) * 4 + ((e_ >> 5) & 3)) * 8 + (d_ >> 4)) * 64 + ((d_ >> 3) & 1) * 32 + (e_ & 31)) * 8 + (d_ & 7);
;             bf16_t* pt = P_PREVT + (size_t)bh * 32 * 32768 + foff;
;             float kvv[32];
; #pragma unroll
;             for (int n = 0; n < 32; ++n) kvv[n] = kv[(size_t)n * 32768];
;             float st = 0.f;
; #pragma unroll
;             for (int n = 0; n < 32; ++n) {
;                 pt[(size_t)n * 32768] = (bf16_t)(pk2(st, 0.f) & 0xffffu);
;                 st = decay * st + kvv[n];
;             }
.LBB0_547:
	v_ashrrev_i32_e32 v0, 15, v4
	v_and_b32_e32 v1, 7, v0
	v_sub_u32_e32 v1, -5, v1
	v_ldexp_f64 v[2:3], 1.0, v1
	v_add_f64 v[2:3], -v[2:3], 1.0
	v_frexp_mant_f64_e32 v[8:9], v[2:3]
	v_cmp_gt_f64_e32 vcc, s[92:93], v[8:9]
	v_frexp_exp_i32_f64_e32 v1, v[2:3]
	v_and_b32_e32 v7, 0x7fff, v4
	v_cndmask_b32_e64 v10, 0, 1, vcc
	v_ldexp_f64 v[8:9], v[8:9], v10
	v_add_f64 v[12:13], v[8:9], 1.0
	v_add_f64 v[14:15], v[12:13], -1.0
	v_add_f64 v[10:11], v[8:9], -1.0
	v_add_f64 v[8:9], v[8:9], -v[14:15]
	v_rcp_f64_e32 v[14:15], v[12:13]
	v_subbrev_co_u32_e32 v1, vcc, 0, v1, vcc
	v_cmp_class_f64_e64 vcc, v[2:3], s85
	v_fma_f64 v[16:17], -v[12:13], v[14:15], 1.0
	v_fmac_f64_e32 v[14:15], v[16:17], v[14:15]
	v_fma_f64 v[16:17], -v[12:13], v[14:15], 1.0
	v_fmac_f64_e32 v[14:15], v[16:17], v[14:15]
	v_mul_f64 v[16:17], v[10:11], v[14:15]
	v_mul_f64 v[18:19], v[12:13], v[16:17]
	v_fma_f64 v[12:13], v[16:17], v[12:13], -v[18:19]
	v_fmac_f64_e32 v[12:13], v[16:17], v[8:9]
	v_add_f64 v[8:9], v[18:19], v[12:13]
	v_add_f64 v[20:21], v[10:11], -v[8:9]
	v_add_f64 v[18:19], v[8:9], -v[18:19]
	v_add_f64 v[10:11], v[10:11], -v[20:21]
	v_add_f64 v[8:9], v[10:11], -v[8:9]
	v_add_f64 v[10:11], v[18:19], -v[12:13]
	v_add_f64 v[8:9], v[10:11], v[8:9]
	v_add_f64 v[8:9], v[20:21], v[8:9]
	v_mul_f64 v[8:9], v[14:15], v[8:9]
	v_add_f64 v[10:11], v[16:17], v[8:9]
	v_add_f64 v[12:13], v[10:11], -v[16:17]
	v_add_f64 v[8:9], v[8:9], -v[12:13]
	v_mul_f64 v[12:13], v[10:11], v[10:11]
	v_mov_b64_e32 v[14:15], v[204:205]
	v_fmac_f64_e32 v[14:15], s[52:53], v[12:13]
	v_mov_b64_e32 v[16:17], v[206:207]
	v_fmac_f64_e32 v[16:17], v[12:13], v[14:15]
	v_mov_b64_e32 v[14:15], v[208:209]
	v_fmac_f64_e32 v[14:15], v[12:13], v[16:17]
	v_mov_b64_e32 v[16:17], v[210:211]
	v_fmac_f64_e32 v[16:17], v[12:13], v[14:15]
	v_mov_b64_e32 v[14:15], v[212:213]
	v_fmac_f64_e32 v[14:15], v[12:13], v[16:17]
	v_mov_b64_e32 v[16:17], v[214:215]
	v_fmac_f64_e32 v[16:17], v[12:13], v[14:15]
	v_ldexp_f64 v[14:15], v[10:11], 1
	v_mul_f64 v[10:11], v[10:11], v[12:13]
	v_mul_f64 v[10:11], v[10:11], v[16:17]
	v_add_f64 v[12:13], v[14:15], v[10:11]
	v_add_f64 v[14:15], v[12:13], -v[14:15]
	v_ldexp_f64 v[8:9], v[8:9], 1
	v_add_f64 v[10:11], v[10:11], -v[14:15]
	v_add_f64 v[8:9], v[8:9], v[10:11]
	v_add_f64 v[10:11], v[12:13], v[8:9]
	v_add_f64 v[12:13], v[10:11], -v[12:13]
	v_mul_f64 v[14:15], v[10:11], s[82:83]
	v_add_f64 v[8:9], v[8:9], -v[12:13]
	v_fma_f64 v[16:17], v[10:11], s[82:83], -v[14:15]
	v_fmac_f64_e32 v[16:17], s[82:83], v[8:9]
	v_fmac_f64_e32 v[16:17], s[88:89], v[10:11]
	v_cvt_f64_i32_e32 v[12:13], v1
	v_add_f64 v[8:9], v[14:15], v[16:17]
	v_add_f64 v[10:11], v[8:9], -v[14:15]
	v_add_f64 v[14:15], v[8:9], v[12:13]
	v_add_f64 v[10:11], v[16:17], -v[10:11]
	v_add_f64 v[16:17], v[14:15], -v[12:13]
	v_add_f64 v[18:19], v[16:17], -v[14:15]
	v_add_f64 v[12:13], v[18:19], v[12:13]
	v_add_f64 v[8:9], v[8:9], -v[16:17]
	v_add_f64 v[8:9], v[8:9], v[12:13]
	v_add_f64 v[8:9], v[10:11], v[8:9]
	v_add_f64 v[8:9], v[14:15], v[8:9]
	v_cndmask_b32_e32 v1, v8, v2, vcc
	v_cndmask_b32_e32 v8, v9, v3, vcc
	v_cmp_ngt_f64_e32 vcc, 0, v[2:3]
	v_lshlrev_b32_e32 v192, 2, v7
	v_lshrrev_b32_e32 v7, 3, v4
	v_cndmask_b32_e32 v9, v241, v8, vcc
	v_cmp_nge_f64_e32 vcc, 0, v[2:3]
	v_and_b32_e32 v7, 0xe00, v7
	s_mov_b32 s12, 0x1e0000
	v_cndmask_b32_e32 v8, 0, v1, vcc
	v_cmp_neq_f64_e32 vcc, 0, v[2:3]
	s_nop 1
	v_cndmask_b32_e32 v9, v235, v9, vcc
	v_cvt_f32_f64_e32 v1, v[8:9]
	v_mul_f32_e32 v10, 0x43000000, v1
	v_ashrrev_i32_e32 v1, 31, v0
	v_lshlrev_b64 v[2:3], 22, v[0:1]
	v_lshl_add_u64 v[2:3], s[8:9], 0, v[2:3]
	v_lshl_add_u64 v[2:3], v[2:3], 0, v[192:193]
	v_and_b32_e32 v8, 0x1e0, v5
	v_bfe_u32 v9, v4, 7, 5
	v_or3_b32 v7, v7, v8, v9
	global_load_dword v11, v[2:3], off nt
	v_add_co_u32_e32 v8, vcc, s50, v2
	v_exp_f32_e32 v10, v10
	s_nop 0
	v_addc_co_u32_e32 v9, vcc, 0, v3, vcc
	global_load_dword v12, v[8:9], off nt
	v_add_co_u32_e32 v8, vcc, s54, v2
	v_lshlrev_b64 v[0:1], 21, v[0:1]
	s_nop 0
	v_addc_co_u32_e32 v9, vcc, 0, v3, vcc
	global_load_dword v13, v[8:9], off nt
	v_add_co_u32_e32 v8, vcc, s95, v2
	v_lshl_add_u64 v[0:1], s[10:11], 0, v[0:1]
	s_nop 0
	v_addc_co_u32_e32 v9, vcc, 0, v3, vcc
	global_load_dword v14, v[8:9], off nt
	v_add_co_u32_e32 v8, vcc, s19, v2
	v_lshl_or_b32 v192, v7, 4, v6
	s_nop 0
	v_addc_co_u32_e32 v9, vcc, 0, v3, vcc
	global_load_dword v15, v[8:9], off nt
	v_add_co_u32_e32 v8, vcc, s20, v2
	v_lshl_add_u64 v[0:1], v[0:1], 0, v[192:193]
	s_nop 0
	v_addc_co_u32_e32 v9, vcc, 0, v3, vcc
	global_load_dword v16, v[8:9], off nt
	v_add_co_u32_e32 v8, vcc, s21, v2
	global_store_short v[0:1], v193, off
	s_nop 0
	v_addc_co_u32_e32 v9, vcc, 0, v3, vcc
	global_load_dword v17, v[8:9], off nt
	v_add_co_u32_e32 v8, vcc, s22, v2
	v_add_u32_e32 v4, s4, v4
	s_nop 0
	v_addc_co_u32_e32 v9, vcc, 0, v3, vcc
	global_load_dword v18, v[8:9], off nt
	v_add_co_u32_e32 v8, vcc, s23, v2
	v_add_u32_e32 v5, s5, v5
	s_nop 0
	v_addc_co_u32_e32 v9, vcc, 0, v3, vcc
	global_load_dword v19, v[8:9], off nt
	v_add_co_u32_e32 v8, vcc, s24, v2
	s_waitcnt vmcnt(0)
; __device__ __forceinline__ unsigned pk2(float lo, float hi) { f32x2 f = {lo, hi}; bf16x2_t b = __builtin_convertvector(f, bf16x2_t); return __builtin_bit_cast(unsigned, b); }
; __global__ void __launch_bounds__(512, 2) mega_fwd(Params p) {
;     ...
;             float kvv[32];
; #pragma unroll
;             for (int n = 0; n < 32; ++n) kvv[n] = kv[(size_t)n * 32768];
;             float st = 0.f;
; #pragma unroll
;             for (int n = 0; n < 32; ++n) {
;                 pt[(size_t)n * 32768] = (bf16_t)(pk2(st, 0.f) & 0xffffu);
;                 st = decay * st + kvv[n];
;             }
	v_fmac_f32_e32 v11, 0, v10
	v_addc_co_u32_e32 v9, vcc, 0, v3, vcc
	global_load_dword v20, v[8:9], off nt
	v_add_co_u32_e32 v8, vcc, s25, v2
	v_cvt_pk_bf16_f32 v7, v11, s0
	s_nop 0
	v_addc_co_u32_e32 v9, vcc, 0, v3, vcc
	global_load_dword v21, v[8:9], off nt
	v_add_co_u32_e32 v8, vcc, s26, v2
	v_fmac_f32_e32 v12, v10, v11
	s_nop 0
	v_addc_co_u32_e32 v9, vcc, 0, v3, vcc
	global_load_dword v22, v[8:9], off nt
	v_add_co_u32_e32 v8, vcc, s27, v2
	v_fmac_f32_e32 v13, v10, v12
	s_nop 0
	v_addc_co_u32_e32 v9, vcc, 0, v3, vcc
	global_load_dword v23, v[8:9], off nt
	v_add_co_u32_e32 v8, vcc, s18, v2
	v_fmac_f32_e32 v14, v10, v13
	s_nop 0
	v_addc_co_u32_e32 v9, vcc, 0, v3, vcc
	global_load_dword v24, v[8:9], off nt
	v_add_co_u32_e32 v8, vcc, s28, v2
	v_fmac_f32_e32 v15, v10, v14
	s_nop 0
	v_addc_co_u32_e32 v9, vcc, 0, v3, vcc
	global_load_dword v25, v[8:9], off nt
	v_add_co_u32_e32 v8, vcc, s12, v2
	s_mov_b32 s12, 0x200000
	s_nop 0
	v_addc_co_u32_e32 v9, vcc, 0, v3, vcc
	global_load_dword v26, v[8:9], off nt
	v_add_co_u32_e32 v8, vcc, s12, v2
	s_mov_b32 s12, 0x220000
	s_nop 0
	v_addc_co_u32_e32 v9, vcc, 0, v3, vcc
	global_load_dword v27, v[8:9], off nt
	v_add_co_u32_e32 v8, vcc, s12, v2
	s_mov_b32 s12, 0x240000
	s_nop 0
	v_addc_co_u32_e32 v9, vcc, 0, v3, vcc
	global_load_dword v28, v[8:9], off nt
	v_add_co_u32_e32 v8, vcc, s12, v2
	s_mov_b32 s12, 0x260000
	s_nop 0
	v_addc_co_u32_e32 v9, vcc, 0, v3, vcc
	global_load_dword v29, v[8:9], off nt
	v_add_co_u32_e32 v8, vcc, s12, v2
	s_mov_b32 s12, 0x280000
	s_nop 0
	v_addc_co_u32_e32 v9, vcc, 0, v3, vcc
	global_load_dword v30, v[8:9], off nt
	v_add_co_u32_e32 v8, vcc, s12, v2
	s_mov_b32 s12, 0x2a0000
	s_nop 0
	v_addc_co_u32_e32 v9, vcc, 0, v3, vcc
	global_load_dword v31, v[8:9], off nt
	v_add_co_u32_e32 v8, vcc, s12, v2
	s_mov_b32 s12, 0x2c0000
	s_nop 0
	v_addc_co_u32_e32 v9, vcc, 0, v3, vcc
	global_load_dword v32, v[8:9], off nt
	v_add_co_u32_e32 v8, vcc, s12, v2
	s_mov_b32 s12, 0x2e0000
	s_nop 0
	v_addc_co_u32_e32 v9, vcc, 0, v3, vcc
	global_load_dword v33, v[8:9], off nt
	v_add_co_u32_e32 v8, vcc, s12, v2
	s_mov_b32 s12, 0x300000
	s_nop 0
	v_addc_co_u32_e32 v9, vcc, 0, v3, vcc
	global_load_dword v34, v[8:9], off nt
	v_add_co_u32_e32 v8, vcc, s12, v2
	s_mov_b32 s12, 0x320000
	s_nop 0
	v_addc_co_u32_e32 v9, vcc, 0, v3, vcc
	global_load_dword v35, v[8:9], off nt
	v_add_co_u32_e32 v8, vcc, s12, v2
	s_mov_b32 s12, 0x340000
	s_nop 0
	v_addc_co_u32_e32 v9, vcc, 0, v3, vcc
	global_load_dword v36, v[8:9], off nt
	v_add_co_u32_e32 v8, vcc, s12, v2
	s_mov_b32 s12, 0x360000
	s_nop 0
	v_addc_co_u32_e32 v9, vcc, 0, v3, vcc
	global_load_dword v37, v[8:9], off nt
	v_add_co_u32_e32 v8, vcc, s12, v2
	s_mov_b32 s12, 0x380000
	s_nop 0
	v_addc_co_u32_e32 v9, vcc, 0, v3, vcc
	global_load_dword v38, v[8:9], off nt
	v_add_co_u32_e32 v8, vcc, s12, v2
	s_mov_b32 s12, 0x3a0000
	s_nop 0
	v_addc_co_u32_e32 v9, vcc, 0, v3, vcc
	global_load_dword v39, v[8:9], off nt
	v_add_co_u32_e32 v8, vcc, s12, v2
	s_mov_b32 s12, 0x3c0000
	s_nop 0
	v_addc_co_u32_e32 v9, vcc, 0, v3, vcc
	v_add_co_u32_e32 v2, vcc, s12, v2
	global_load_dword v8, v[8:9], off nt
	s_nop 0
	v_addc_co_u32_e32 v3, vcc, 0, v3, vcc
	global_load_dword v9, v[2:3], off nt
	v_add_co_u32_e32 v2, vcc, s49, v0
	v_fmac_f32_e32 v16, v10, v15
	s_nop 0
	v_addc_co_u32_e32 v3, vcc, 0, v1, vcc
	global_store_short v[2:3], v7, off
	v_add_co_u32_e32 v2, vcc, s50, v0
	v_cvt_pk_bf16_f32 v7, v12, s0
	s_nop 0
	v_addc_co_u32_e32 v3, vcc, 0, v1, vcc
	global_store_short v[2:3], v7, off
	v_add_co_u32_e32 v2, vcc, s79, v0
	v_cvt_pk_bf16_f32 v7, v13, s0
	s_nop 0
	v_addc_co_u32_e32 v3, vcc, 0, v1, vcc
	global_store_short v[2:3], v7, off
	v_add_co_u32_e32 v2, vcc, s54, v0
	v_cvt_pk_bf16_f32 v7, v14, s0
	s_nop 0
	v_addc_co_u32_e32 v3, vcc, 0, v1, vcc
	global_store_short v[2:3], v7, off
	v_add_co_u32_e32 v2, vcc, s13, v0
	v_cvt_pk_bf16_f32 v7, v15, s0
	s_nop 0
	v_addc_co_u32_e32 v3, vcc, 0, v1, vcc
	global_store_short v[2:3], v7, off
	v_add_co_u32_e32 v2, vcc, s95, v0
	v_cvt_pk_bf16_f32 v7, v16, s0
	s_nop 0
	v_addc_co_u32_e32 v3, vcc, 0, v1, vcc
	global_store_short v[2:3], v7, off
	v_fmac_f32_e32 v17, v10, v16
	v_add_co_u32_e32 v2, vcc, s14, v0
	v_cvt_pk_bf16_f32 v7, v17, s0
	s_nop 0
	v_addc_co_u32_e32 v3, vcc, 0, v1, vcc
	global_store_short v[2:3], v7, off
	v_fmac_f32_e32 v18, v10, v17
	v_add_co_u32_e32 v2, vcc, s19, v0
	v_cvt_pk_bf16_f32 v7, v18, s0
	s_nop 0
	v_addc_co_u32_e32 v3, vcc, 0, v1, vcc
	s_mov_b32 s12, 0x90000
	global_store_short v[2:3], v7, off
	v_fmac_f32_e32 v19, v10, v18
	v_add_co_u32_e32 v2, vcc, s12, v0
	v_cvt_pk_bf16_f32 v7, v19, s0
	s_nop 0
	v_addc_co_u32_e32 v3, vcc, 0, v1, vcc
	global_store_short v[2:3], v7, off
	s_waitcnt vmcnt(30)
; __device__ __forceinline__ unsigned pk2(float lo, float hi) { f32x2 f = {lo, hi}; bf16x2_t b = __builtin_convertvector(f, bf16x2_t); return __builtin_bit_cast(unsigned, b); }
; __global__ void __launch_bounds__(512, 2) mega_fwd(Params p) {
;     ...
;             float st = 0.f;
; #pragma unroll
;             for (int n = 0; n < 32; ++n) {
;                 pt[(size_t)n * 32768] = (bf16_t)(pk2(st, 0.f) & 0xffffu);
;                 st = decay * st + kvv[n];
;             }
	v_fmac_f32_e32 v20, v10, v19
	v_add_co_u32_e32 v2, vcc, s20, v0
	v_cvt_pk_bf16_f32 v7, v20, s0
	s_nop 0
	v_addc_co_u32_e32 v3, vcc, 0, v1, vcc
	s_mov_b32 s12, 0xb0000
	global_store_short v[2:3], v7, off
	s_waitcnt vmcnt(30)
	v_fmac_f32_e32 v21, v10, v20
	v_add_co_u32_e32 v2, vcc, s12, v0
	v_cvt_pk_bf16_f32 v7, v21, s0
	s_nop 0
	v_addc_co_u32_e32 v3, vcc, 0, v1, vcc
	global_store_short v[2:3], v7, off
	s_waitcnt vmcnt(30)
	v_fmac_f32_e32 v22, v10, v21
	v_add_co_u32_e32 v2, vcc, s21, v0
	v_cvt_pk_bf16_f32 v7, v22, s0
	s_nop 0
	v_addc_co_u32_e32 v3, vcc, 0, v1, vcc
	global_store_short v[2:3], v7, off
	s_waitcnt vmcnt(30)
	v_fmac_f32_e32 v23, v10, v22
	v_add_co_u32_e32 v2, vcc, s15, v0
	v_cvt_pk_bf16_f32 v7, v23, s0
	s_nop 0
	v_addc_co_u32_e32 v3, vcc, 0, v1, vcc
	global_store_short v[2:3], v7, off
	s_waitcnt vmcnt(30)
	v_fmac_f32_e32 v24, v10, v23
	v_add_co_u32_e32 v2, vcc, s22, v0
	v_cvt_pk_bf16_f32 v7, v24, s0
	s_nop 0
	v_addc_co_u32_e32 v3, vcc, 0, v1, vcc
	s_mov_b32 s12, 0xf0000
	global_store_short v[2:3], v7, off
	s_waitcnt vmcnt(30)
	v_fmac_f32_e32 v25, v10, v24
	v_add_co_u32_e32 v2, vcc, s12, v0
	v_cvt_pk_bf16_f32 v7, v25, s0
	s_nop 0
	v_addc_co_u32_e32 v3, vcc, 0, v1, vcc
	global_store_short v[2:3], v7, off
	s_waitcnt vmcnt(30)
	v_fmac_f32_e32 v26, v10, v25
	v_add_co_u32_e32 v2, vcc, s23, v0
	v_cvt_pk_bf16_f32 v7, v26, s0
	s_nop 0
	v_addc_co_u32_e32 v3, vcc, 0, v1, vcc
	s_mov_b32 s12, 0x110000
	global_store_short v[2:3], v7, off
	s_waitcnt vmcnt(30)
	v_fmac_f32_e32 v27, v10, v26
	v_add_co_u32_e32 v2, vcc, s12, v0
	v_cvt_pk_bf16_f32 v7, v27, s0
	s_nop 0
	v_addc_co_u32_e32 v3, vcc, 0, v1, vcc
	global_store_short v[2:3], v7, off
	s_waitcnt vmcnt(30)
	v_fmac_f32_e32 v28, v10, v27
	v_add_co_u32_e32 v2, vcc, s24, v0
	v_cvt_pk_bf16_f32 v7, v28, s0
	s_nop 0
	v_addc_co_u32_e32 v3, vcc, 0, v1, vcc
	s_mov_b32 s12, 0x130000
	global_store_short v[2:3], v7, off
	s_waitcnt vmcnt(30)
	v_fmac_f32_e32 v29, v10, v28
	v_add_co_u32_e32 v2, vcc, s12, v0
	v_cvt_pk_bf16_f32 v7, v29, s0
	s_nop 0
	v_addc_co_u32_e32 v3, vcc, 0, v1, vcc
	global_store_short v[2:3], v7, off
	s_waitcnt vmcnt(30)
	v_fmac_f32_e32 v30, v10, v29
	v_add_co_u32_e32 v2, vcc, s25, v0
	v_cvt_pk_bf16_f32 v7, v30, s0
	s_nop 0
	v_addc_co_u32_e32 v3, vcc, 0, v1, vcc
	s_mov_b32 s12, 0x150000
	global_store_short v[2:3], v7, off
	s_waitcnt vmcnt(30)
	v_fmac_f32_e32 v31, v10, v30
	v_add_co_u32_e32 v2, vcc, s12, v0
	v_cvt_pk_bf16_f32 v7, v31, s0
	s_nop 0
	v_addc_co_u32_e32 v3, vcc, 0, v1, vcc
	global_store_short v[2:3], v7, off
	s_waitcnt vmcnt(30)
	v_fmac_f32_e32 v32, v10, v31
	v_add_co_u32_e32 v2, vcc, s26, v0
	v_cvt_pk_bf16_f32 v7, v32, s0
	s_nop 0
	v_addc_co_u32_e32 v3, vcc, 0, v1, vcc
	s_mov_b32 s12, 0x170000
	global_store_short v[2:3], v7, off
	s_waitcnt vmcnt(30)
	v_fmac_f32_e32 v33, v10, v32
	v_add_co_u32_e32 v2, vcc, s12, v0
	v_cvt_pk_bf16_f32 v7, v33, s0
	s_nop 0
	v_addc_co_u32_e32 v3, vcc, 0, v1, vcc
	global_store_short v[2:3], v7, off
	s_waitcnt vmcnt(30)
	v_fmac_f32_e32 v34, v10, v33
	v_add_co_u32_e32 v2, vcc, s27, v0
	v_cvt_pk_bf16_f32 v7, v34, s0
	s_nop 0
	v_addc_co_u32_e32 v3, vcc, 0, v1, vcc
	s_mov_b32 s12, 0x190000
	global_store_short v[2:3], v7, off
	s_waitcnt vmcnt(30)
	v_fmac_f32_e32 v35, v10, v34
	v_add_co_u32_e32 v2, vcc, s12, v0
	v_cvt_pk_bf16_f32 v7, v35, s0
	s_nop 0
	v_addc_co_u32_e32 v3, vcc, 0, v1, vcc
	global_store_short v[2:3], v7, off
	s_waitcnt vmcnt(30)
	v_fmac_f32_e32 v36, v10, v35
	v_add_co_u32_e32 v2, vcc, s18, v0
	v_cvt_pk_bf16_f32 v7, v36, s0
	s_nop 0
	v_addc_co_u32_e32 v3, vcc, 0, v1, vcc
	s_mov_b32 s12, 0x1b0000
	global_store_short v[2:3], v7, off
	s_waitcnt vmcnt(30)
	v_fmac_f32_e32 v37, v10, v36
	v_add_co_u32_e32 v2, vcc, s12, v0
	v_cvt_pk_bf16_f32 v7, v37, s0
	s_nop 0
	v_addc_co_u32_e32 v3, vcc, 0, v1, vcc
	global_store_short v[2:3], v7, off
	s_waitcnt vmcnt(30)
	v_fmac_f32_e32 v38, v10, v37
	v_add_co_u32_e32 v2, vcc, s28, v0
	v_cvt_pk_bf16_f32 v7, v38, s0
	s_nop 0
	v_addc_co_u32_e32 v3, vcc, 0, v1, vcc
	global_store_short v[2:3], v7, off
	s_waitcnt vmcnt(30)
	v_fmac_f32_e32 v39, v10, v38
	v_add_co_u32_e32 v2, vcc, 0x1d0000, v0
	v_cvt_pk_bf16_f32 v7, v39, s0
	s_nop 0
	v_addc_co_u32_e32 v3, vcc, 0, v1, vcc
	global_store_short v[2:3], v7, off
	v_add_co_u32_e32 v2, vcc, 0x1e0000, v0
	s_waitcnt vmcnt(30)
	v_fmac_f32_e32 v8, v10, v39
	v_addc_co_u32_e32 v3, vcc, 0, v1, vcc
	v_add_co_u32_e32 v0, vcc, 0x1f0000, v0
	s_mov_b32 s12, 0x7ffff
	s_nop 0
	v_addc_co_u32_e32 v1, vcc, 0, v1, vcc
	v_cvt_pk_bf16_f32 v7, v8, s0
	s_waitcnt vmcnt(29)
	v_fmac_f32_e32 v9, v10, v8
	v_cmp_lt_i32_e32 vcc, s12, v4
	global_store_short v[2:3], v7, off
	v_cvt_pk_bf16_f32 v2, v9, s0
	s_or_b64 s[16:17], vcc, s[16:17]
	global_store_short v[0:1], v2, off
	s_andn2_b64 exec, exec, s[16:17]
	s_cbranch_execnz .LBB0_547

; #define PHASE_ENV unsigned char* ws = opq_ptr(p.ws); const int G = opq_int((int)gridDim.x), ngw = G * 8; (void)ws; (void)ngw
; template <bool F32OUT>
; __device__ __forceinline__ void rms_row(const float* xrow, const float* g, void* orow, int lane) {
;     const f32x4* xr = (const f32x4*)xrow + lane;
;     f32x4 v[8]; float s = 0.f;
; #pragma unroll
;     for (int j = 0; j < 8; ++j) { v[j] = xr[64 * j]; s += (v[j].x * v[j].x + v[j].y * v[j].y) + (v[j].z * v[j].z + v[j].w * v[j].w); }
;     const float rstd = 1.0f / sqrtf(wave_sum(s) * (1.0f / D) + 1e-6f);
; __global__ void __launch_bounds__(512, 2) mega_fwd(Params p) {
;     ...
;     { PHASE_IDS; PHASE_ENV;
;     for (int m = gw; m < M; m += ngw) rms_row<true>(P_X + (size_t)m * D, p.in[14], p.out + (size_t)m * D, lane); }
.LBB0_957:
	s_nop 0
	v_lshl_add_u64 v[0:1], s[6:7], 0, v[16:17]
	v_add_co_u32_e64 v58, s[0:1], s3, v0
	v_add_co_u32_e32 v56, vcc, 0xcc00000, v0
	s_nop 0
	v_addc_co_u32_e64 v59, s[0:1], 0, v1, s[0:1]
	v_addc_co_u32_e32 v57, vcc, 0, v1, vcc
	global_load_dwordx4 v[4:7], v[58:59], off
	global_load_dwordx4 v[12:15], v[58:59], off offset:1024
	global_load_dwordx4 v[8:11], v[58:59], off offset:2048
	global_load_dwordx4 v[36:39], v[56:57], off
	global_load_dwordx4 v[40:43], v[56:57], off offset:1024
	global_load_dwordx4 v[44:47], v[56:57], off offset:2048
	global_load_dwordx4 v[48:51], v[56:57], off offset:3072
	global_load_dwordx4 v[0:3], v[58:59], off offset:3072
	global_load_dwordx4 v[52:55], v[18:19], off
	v_lshl_add_u64 v[56:57], s[10:11], 0, v[16:17]
	s_add_i32 s2, s2, s4
	s_add_u32 s6, s6, s8
	s_addc_u32 s7, s7, s9
	s_add_u32 s10, s10, s8
	s_addc_u32 s11, s11, s9
	s_cmpk_gt_i32 s2, 0x1fff
	s_waitcnt vmcnt(0)
	v_mul_f32_e32 v81, v4, v4
	v_pk_mul_f32 v[58:59], v[14:15], v[14:15]
	v_pk_mul_f32 v[60:61], v[12:13], v[12:13]
	v_mul_f32_e32 v62, v9, v9
	v_mul_f32_e32 v64, v11, v11
	v_mov_b32_e32 v68, v37
	v_mov_b32_e32 v69, v41
	v_mov_b32_e32 v72, v39
	v_mov_b32_e32 v73, v43
	v_mul_f32_e32 v89, v2, v2
	v_mul_f32_e32 v90, v3, v3
	v_mov_b32_e32 v66, v36
	v_mov_b32_e32 v67, v40
	v_mov_b32_e32 v70, v38
	v_mov_b32_e32 v71, v42
	v_pk_mul_f32 v[74:75], v[46:47], v[46:47]
	v_pk_mul_f32 v[76:77], v[44:45], v[44:45]
	v_pk_mov_b32 v[82:83], v[60:61], v[58:59] op_sel:[1,0]
	v_mov_b32_e32 v61, v59
	v_pk_fma_f32 v[58:59], v[8:9], v[8:9], v[62:63] op_sel_hi:[1,1,0]
	v_pk_fma_f32 v[62:63], v[10:11], v[10:11], v[64:65] op_sel_hi:[1,1,0]
	v_pk_mul_f32 v[64:65], v[68:69], v[68:69]
	v_pk_mul_f32 v[68:69], v[72:73], v[72:73]
	v_pk_mov_b32 v[72:73], v[76:77], v[74:75] op_sel:[1,0]
	v_mov_b32_e32 v77, v75
	v_mov_b32_e32 v59, v89
	v_mov_b32_e32 v63, v90
	v_pk_fma_f32 v[64:65], v[66:67], v[66:67], v[64:65]
	v_pk_fma_f32 v[66:67], v[70:71], v[70:71], v[68:69]
	v_mul_f32_e32 v78, v49, v49
	v_mul_f32_e32 v80, v51, v51
	v_pk_add_f32 v[68:69], v[72:73], v[76:77]
	v_pk_add_f32 v[58:59], v[58:59], v[62:63]
	v_pk_add_f32 v[62:63], v[64:65], v[66:67]
	v_mul_f32_e32 v84, v5, v5
	v_mul_f32_e32 v85, v6, v6
	v_mul_f32_e32 v86, v7, v7
	v_pk_fma_f32 v[74:75], v[48:49], v[48:49], v[78:79] op_sel_hi:[1,1,0]
	v_pk_fma_f32 v[78:79], v[50:51], v[50:51], v[80:81] op_sel_hi:[1,1,0]
	v_pk_add_f32 v[64:65], v[68:69], v[68:69] op_sel:[0,1] op_sel_hi:[1,0]
	v_pk_add_f32 v[62:63], v[62:63], v[62:63] op_sel:[0,1] op_sel_hi:[1,0]
	v_mov_b32_e32 v75, v85
	v_mov_b32_e32 v79, v86
	v_mov_b32_e32 v65, v84
	v_mov_b32_e32 v63, v81
	v_pk_add_f32 v[66:67], v[74:75], v[78:79]
	v_pk_add_f32 v[62:63], v[62:63], v[64:65]
	v_pk_add_f32 v[60:61], v[82:83], v[60:61]
	v_pk_add_f32 v[62:63], v[62:63], v[66:67]
	v_mul_f32_e32 v87, v0, v0
	v_mul_f32_e32 v88, v1, v1
	v_pk_add_f32 v[60:61], v[60:61], v[60:61] op_sel:[0,1] op_sel_hi:[1,0]
	v_pk_add_f32 v[62:63], v[62:63], v[62:63] op_sel:[0,1] op_sel_hi:[1,0]
	v_mov_b32_e32 v61, v88
	v_mov_b32_e32 v63, v87
	v_pk_add_f32 v[60:61], v[62:63], v[60:61]
	s_nop 0
	v_pk_add_f32 v[58:59], v[60:61], v[58:59]
	s_nop 0
	v_add_f32_e32 v58, v58, v59
	ds_bpermute_b32 v59, v28, v58
	s_waitcnt lgkmcnt(0)
	v_add_f32_e32 v58, v58, v59
	ds_bpermute_b32 v59, v29, v58
	s_waitcnt lgkmcnt(0)
	v_add_f32_e32 v58, v58, v59
	ds_bpermute_b32 v59, v30, v58
	s_waitcnt lgkmcnt(0)
	v_add_f32_e32 v58, v58, v59
	ds_bpermute_b32 v59, v31, v58
	s_waitcnt lgkmcnt(0)
	v_add_f32_e32 v58, v58, v59
	ds_bpermute_b32 v59, v32, v58
	s_waitcnt lgkmcnt(0)
	v_add_f32_e32 v58, v58, v59
	ds_bpermute_b32 v59, v33, v58
	s_waitcnt lgkmcnt(0)
; __device__ __forceinline__ unsigned pk2(float lo, float hi) { f32x2 f = {lo, hi}; bf16x2_t b = __builtin_convertvector(f, bf16x2_t); return __builtin_bit_cast(unsigned, b); }
; template <bool F32OUT>
; __device__ __forceinline__ void rms_row(const float* xrow, const float* g, void* orow, int lane) {
;     ...
;     const float rstd = 1.0f / sqrtf(wave_sum(s) * (1.0f / D) + 1e-6f);
;     const f32x4* gr = (const f32x4*)g + lane;
; #pragma unroll
;     for (int j = 0; j < 8; ++j) {
;         const f32x4 gg = gr[64 * j];
;         const f32x4 o = v[j] * rstd * gg;
;         if (F32OUT) ((f32x4*)orow)[lane + 64 * j] = o;
;         else { u32x2 w; w.x = pk2(o.x, o.y); w.y = pk2(o.z, o.w); ((u32x2*)orow)[lane + 64 * j] = w; }
;     }
	v_add_f32_e32 v58, v58, v59
	v_fmamk_f32 v58, v58, 0x3a000000, v34
	v_mul_f32_e32 v59, 0x4f800000, v58
	v_cmp_gt_f32_e32 vcc, s5, v58
	s_nop 1
	v_cndmask_b32_e32 v58, v58, v59, vcc
	v_sqrt_f32_e32 v59, v58
	s_nop 0
	v_add_u32_e32 v60, -1, v59
	v_add_u32_e32 v61, 1, v59
	v_fma_f32 v62, -v60, v59, v58
	v_fma_f32 v63, -v61, v59, v58
	v_cmp_ge_f32_e64 s[0:1], 0, v62
	s_nop 1
	v_cndmask_b32_e64 v59, v59, v60, s[0:1]
	v_cmp_lt_f32_e64 s[0:1], 0, v63
	s_nop 1
	v_cndmask_b32_e64 v59, v59, v61, s[0:1]
	v_mul_f32_e32 v60, 0x37800000, v59
	v_cndmask_b32_e32 v59, v59, v60, vcc
	v_cmp_class_f32_e32 vcc, v58, v35
	s_nop 1
	v_cndmask_b32_e32 v58, v59, v58, vcc
	v_div_scale_f32 v59, s[0:1], v58, v58, 1.0
	v_rcp_f32_e32 v61, v59
	v_div_scale_f32 v60, vcc, 1.0, v58, 1.0
	v_fma_f32 v62, -v59, v61, 1.0
	v_fmac_f32_e32 v61, v62, v61
	v_mul_f32_e32 v62, v60, v61
	v_fma_f32 v63, -v59, v62, v60
	v_fmac_f32_e32 v62, v63, v61
	v_fma_f32 v59, -v59, v62, v60
	v_div_fmas_f32 v59, v59, v61, v62
	v_div_fixup_f32 v58, v59, v58, 1.0
	v_pk_mul_f32 v[36:37], v[36:37], v[58:59] op_sel_hi:[1,0]
	v_pk_mul_f32 v[38:39], v[38:39], v[58:59] op_sel_hi:[1,0]
	v_pk_mul_f32 v[36:37], v[52:53], v[36:37]
	v_pk_mul_f32 v[38:39], v[54:55], v[38:39]
	global_store_dwordx4 v[56:57], v[36:39], off nt
	global_load_dwordx4 v[36:39], v[18:19], off offset:1024
	v_pk_mul_f32 v[42:43], v[42:43], v[58:59] op_sel_hi:[1,0]
	v_pk_mul_f32 v[40:41], v[40:41], v[58:59] op_sel_hi:[1,0]
	v_pk_mul_f32 v[6:7], v[6:7], v[58:59] op_sel_hi:[1,0]
	v_pk_mul_f32 v[4:5], v[4:5], v[58:59] op_sel_hi:[1,0]
	v_pk_mul_f32 v[14:15], v[14:15], v[58:59] op_sel_hi:[1,0]
	v_pk_mul_f32 v[12:13], v[12:13], v[58:59] op_sel_hi:[1,0]
	v_pk_mul_f32 v[10:11], v[10:11], v[58:59] op_sel_hi:[1,0]
	v_pk_mul_f32 v[8:9], v[8:9], v[58:59] op_sel_hi:[1,0]
	v_pk_mul_f32 v[2:3], v[2:3], v[58:59] op_sel_hi:[1,0]
	v_pk_mul_f32 v[0:1], v[0:1], v[58:59] op_sel_hi:[1,0]
	s_waitcnt vmcnt(0)
	v_pk_mul_f32 v[36:37], v[36:37], v[40:41]
	v_pk_mul_f32 v[38:39], v[38:39], v[42:43]
	global_store_dwordx4 v[56:57], v[36:39], off offset:1024 nt
	global_load_dwordx4 v[36:39], v[18:19], off offset:2048
	v_pk_mul_f32 v[40:41], v[46:47], v[58:59] op_sel_hi:[1,0]
	v_pk_mul_f32 v[42:43], v[44:45], v[58:59] op_sel_hi:[1,0]
	s_waitcnt vmcnt(0)
	v_pk_mul_f32 v[38:39], v[38:39], v[40:41]
	v_pk_mul_f32 v[36:37], v[36:37], v[42:43]
	global_store_dwordx4 v[56:57], v[36:39], off offset:2048 nt
	global_load_dwordx4 v[36:39], v[18:19], off offset:3072
	v_pk_mul_f32 v[40:41], v[50:51], v[58:59] op_sel_hi:[1,0]
	v_pk_mul_f32 v[42:43], v[48:49], v[58:59] op_sel_hi:[1,0]
	s_waitcnt vmcnt(0)
	v_pk_mul_f32 v[38:39], v[38:39], v[40:41]
	v_pk_mul_f32 v[36:37], v[36:37], v[42:43]
	global_store_dwordx4 v[56:57], v[36:39], off offset:3072 nt
	global_load_dwordx4 v[36:39], v[20:21], off
	v_add_co_u32_e32 v40, vcc, s12, v56
	s_waitcnt vmcnt(0)
	v_pk_mul_f32 v[4:5], v[36:37], v[4:5]
	v_addc_co_u32_e32 v41, vcc, 0, v57, vcc
	v_pk_mul_f32 v[6:7], v[38:39], v[6:7]
	global_store_dwordx4 v[40:41], v[4:7], off nt
	global_load_dwordx4 v[4:7], v[22:23], off
	s_waitcnt vmcnt(0)
	v_pk_mul_f32 v[4:5], v[12:13], v[4:5]
	v_pk_mul_f32 v[6:7], v[14:15], v[6:7]
	global_store_dwordx4 v[40:41], v[4:7], off offset:1024 nt
	global_load_dwordx4 v[4:7], v[24:25], off
	s_waitcnt vmcnt(0)
	v_pk_mul_f32 v[4:5], v[8:9], v[4:5]
	v_pk_mul_f32 v[6:7], v[10:11], v[6:7]
	global_store_dwordx4 v[40:41], v[4:7], off offset:2048 nt
	global_load_dwordx4 v[4:7], v[26:27], off
	s_waitcnt vmcnt(0)
	v_pk_mul_f32 v[0:1], v[0:1], v[4:5]
	v_pk_mul_f32 v[2:3], v[2:3], v[6:7]
	global_store_dwordx4 v[40:41], v[0:3], off offset:3072 nt
	s_cbranch_scc0 .LBB0_957
